# P8 top-k cross-row exchanges: mov+swap+med3 instead of mov,mov,swap,cndmask,med3
# baseline (speedup 1.0000x reference)
.LBB0_922:
	s_waitcnt lgkmcnt(0)
	v_lshl_add_u64 v[2:3], v[0:1], 0, s[64:65]
	v_add_co_u32_e32 v60, vcc, 0x8008000, v2
	s_nop 1
	v_addc_co_u32_e32 v61, vcc, 0, v3, vcc
	global_load_dword v59, v[60:61], off
	global_load_dword v62, v[60:61], off offset:256
	global_load_dword v63, v[60:61], off offset:512
	s_nop 0
	global_load_dword v60, v[60:61], off offset:768
	s_waitcnt vmcnt(3)
	v_ashrrev_i32_e32 v61, 31, v59
	v_and_b32_e32 v64, 0xffffff80, v59
	s_waitcnt vmcnt(2)
	v_ashrrev_i32_e32 v65, 31, v62
	s_waitcnt vmcnt(1)
	v_ashrrev_i32_e32 v67, 31, v63
	v_and_b32_e32 v61, 0x7fffff80, v61
	v_and_b32_e32 v66, 0xffffff80, v62
	v_and_b32_e32 v68, 0xffffff80, v63
	v_and_b32_e32 v65, 0x7fffff80, v65
	v_and_b32_e32 v67, 0x7fffff80, v67
	v_bitop3_b32 v61, v61, v164, v64 bitop3:0xde
	v_bitop3_b32 v64, v65, v165, v66 bitop3:0xde
	v_bitop3_b32 v65, v67, v164, v68 bitop3:0xde
	v_mov_b32_dpp v67, v61 quad_perm:[1,0,3,2] row_mask:0xf bank_mask:0xf bound_ctrl:1
	v_mov_b32_dpp v68, v64 quad_perm:[1,0,3,2] row_mask:0xf bank_mask:0xf bound_ctrl:1
	v_med3_i32 v61, v61, v67, v100
	v_med3_i32 v64, v64, v68, v100
	s_waitcnt vmcnt(0)
	v_ashrrev_i32_e32 v69, 31, v60
	v_mov_b32_dpp v67, v61 quad_perm:[2,3,0,1] row_mask:0xf bank_mask:0xf bound_ctrl:1
	v_mov_b32_dpp v68, v64 quad_perm:[2,3,0,1] row_mask:0xf bank_mask:0xf bound_ctrl:1
	v_med3_i32 v61, v61, v67, v101
	v_med3_i32 v64, v64, v68, v101
	v_and_b32_e32 v70, 0xffffff80, v60
	v_mov_b32_dpp v67, v61 quad_perm:[1,0,3,2] row_mask:0xf bank_mask:0xf bound_ctrl:1
	v_mov_b32_dpp v68, v64 quad_perm:[1,0,3,2] row_mask:0xf bank_mask:0xf bound_ctrl:1
	v_med3_i32 v61, v61, v67, v102
	v_and_b32_e32 v69, 0x7fffff80, v69
	v_med3_i32 v64, v64, v68, v102
	v_mov_b32_dpp v67, v61 row_half_mirror row_mask:0xf bank_mask:0xf bound_ctrl:1
	v_bitop3_b32 v66, v69, v165, v70 bitop3:0xde
	v_mov_b32_dpp v68, v64 row_half_mirror row_mask:0xf bank_mask:0xf bound_ctrl:1
	v_mov_b32_dpp v69, v67 quad_perm:[3,2,1,0] row_mask:0xf bank_mask:0xf bound_ctrl:1
	s_nop 0
	v_mov_b32_dpp v67, v68 quad_perm:[3,2,1,0] row_mask:0xf bank_mask:0xf bound_ctrl:1
	v_med3_i32 v61, v61, v69, v103
	v_med3_i32 v64, v64, v67, v103
	s_nop 0
	v_mov_b32_dpp v67, v61 quad_perm:[2,3,0,1] row_mask:0xf bank_mask:0xf bound_ctrl:1
	v_mov_b32_dpp v68, v64 quad_perm:[2,3,0,1] row_mask:0xf bank_mask:0xf bound_ctrl:1
	v_med3_i32 v61, v61, v67, v104
	v_med3_i32 v64, v64, v68, v104
	s_nop 0
	v_mov_b32_dpp v67, v61 quad_perm:[1,0,3,2] row_mask:0xf bank_mask:0xf bound_ctrl:1
	v_mov_b32_dpp v68, v64 quad_perm:[1,0,3,2] row_mask:0xf bank_mask:0xf bound_ctrl:1
	v_med3_i32 v61, v61, v67, v105
	v_med3_i32 v64, v64, v68, v105
	s_nop 0
	v_mov_b32_dpp v67, v61 row_ror:8 row_mask:0xf bank_mask:0xf bound_ctrl:1
	v_mov_b32_dpp v68, v64 row_ror:8 row_mask:0xf bank_mask:0xf bound_ctrl:1
	v_med3_i32 v61, v61, v67, v106
	v_med3_i32 v64, v64, v68, v106
	s_nop 0
	v_mov_b32_dpp v67, v61 row_half_mirror row_mask:0xf bank_mask:0xf bound_ctrl:1
	v_mov_b32_dpp v68, v64 row_half_mirror row_mask:0xf bank_mask:0xf bound_ctrl:1
	s_nop 0
	v_mov_b32_dpp v69, v67 quad_perm:[3,2,1,0] row_mask:0xf bank_mask:0xf bound_ctrl:1
	v_mov_b32_dpp v67, v68 quad_perm:[3,2,1,0] row_mask:0xf bank_mask:0xf bound_ctrl:1
	v_med3_i32 v61, v61, v69, v107
	v_med3_i32 v64, v64, v67, v107
	s_nop 0
	v_mov_b32_dpp v67, v61 quad_perm:[2,3,0,1] row_mask:0xf bank_mask:0xf bound_ctrl:1
	v_mov_b32_dpp v68, v64 quad_perm:[2,3,0,1] row_mask:0xf bank_mask:0xf bound_ctrl:1
	v_med3_i32 v61, v61, v67, v108
	v_med3_i32 v64, v64, v68, v108
	s_nop 0
	v_mov_b32_dpp v67, v61 quad_perm:[1,0,3,2] row_mask:0xf bank_mask:0xf bound_ctrl:1
	v_mov_b32_dpp v68, v64 quad_perm:[1,0,3,2] row_mask:0xf bank_mask:0xf bound_ctrl:1
	v_med3_i32 v61, v61, v67, v109
	v_med3_i32 v64, v64, v68, v109
	v_mov_b32_e32 v67, v61
	v_mov_b32_e32 v68, v61
	v_mov_b32_e32 v69, v64
	v_mov_b32_e32 v70, v64
	v_permlane16_swap_b32_e32 v67, v68
	s_nop 0
	v_permlane16_swap_b32_e32 v69, v70
	v_cndmask_b32_e64 v67, v67, v68, s[6:7]
	v_cndmask_b32_e64 v68, v69, v70, s[6:7]
	v_max_i32_e32 v69, v61, v67
	v_min_i32_e32 v61, v61, v67
	v_cndmask_b32_e64 v61, v61, v69, s[42:43]
	v_med3_i32 v64, v64, v68, v110
	s_nop 0
	v_mov_b32_dpp v67, v61 row_ror:8 row_mask:0xf bank_mask:0xf bound_ctrl:1
	v_mov_b32_dpp v68, v64 row_ror:8 row_mask:0xf bank_mask:0xf bound_ctrl:1
	v_med3_i32 v61, v61, v67, v111
	v_med3_i32 v64, v64, v68, v111
	s_nop 0
	v_mov_b32_dpp v67, v61 row_half_mirror row_mask:0xf bank_mask:0xf bound_ctrl:1
	v_mov_b32_dpp v68, v64 row_half_mirror row_mask:0xf bank_mask:0xf bound_ctrl:1
	s_nop 0
	v_mov_b32_dpp v69, v67 quad_perm:[3,2,1,0] row_mask:0xf bank_mask:0xf bound_ctrl:1
	v_mov_b32_dpp v67, v68 quad_perm:[3,2,1,0] row_mask:0xf bank_mask:0xf bound_ctrl:1
	v_med3_i32 v61, v61, v69, v112
	v_med3_i32 v64, v64, v67, v112
	s_nop 0
	v_mov_b32_dpp v67, v61 quad_perm:[2,3,0,1] row_mask:0xf bank_mask:0xf bound_ctrl:1
	v_med3_i32 v61, v61, v67, v113
	v_mov_b32_dpp v67, v64 quad_perm:[2,3,0,1] row_mask:0xf bank_mask:0xf bound_ctrl:1
	v_med3_i32 v64, v64, v67, v113
	v_mov_b32_dpp v67, v61 quad_perm:[1,0,3,2] row_mask:0xf bank_mask:0xf bound_ctrl:1
	v_med3_i32 v61, v61, v67, v114
	v_mov_b32_dpp v67, v64 quad_perm:[1,0,3,2] row_mask:0xf bank_mask:0xf bound_ctrl:1
	v_med3_i32 v64, v64, v67, v114
	v_mov_b32_e32 v68, v61
	s_nop 1
	v_permlane32_swap_b32_e32 v61, v68
	v_med3_i32 v61, v61, v68, v115
	v_mov_b32_e32 v69, v64
	s_nop 1
	v_permlane32_swap_b32_e32 v64, v69
	v_med3_i32 v64, v64, v69, v116
	v_mov_b32_e32 v68, v61
	s_nop 1
	v_permlane16_swap_b32_e32 v61, v68
	v_med3_i32 v61, v61, v68, v117
	v_mov_b32_e32 v69, v64
	s_nop 1
	v_permlane16_swap_b32_e32 v64, v69
	v_med3_i32 v64, v64, v69, v118
	s_nop 0
	v_mov_b32_dpp v67, v61 row_ror:8 row_mask:0xf bank_mask:0xf bound_ctrl:1
	v_med3_i32 v61, v61, v67, v119
	v_mov_b32_dpp v67, v64 row_ror:8 row_mask:0xf bank_mask:0xf bound_ctrl:1
	v_med3_i32 v64, v64, v67, v120
	v_mov_b32_dpp v67, v61 row_half_mirror row_mask:0xf bank_mask:0xf bound_ctrl:1
	s_nop 0
	v_mov_b32_dpp v68, v64 row_half_mirror row_mask:0xf bank_mask:0xf bound_ctrl:1
	v_mov_b32_dpp v69, v67 quad_perm:[3,2,1,0] row_mask:0xf bank_mask:0xf bound_ctrl:1
	v_med3_i32 v61, v61, v69, v121
	v_mov_b32_dpp v67, v68 quad_perm:[3,2,1,0] row_mask:0xf bank_mask:0xf bound_ctrl:1
	v_med3_i32 v64, v64, v67, v122
	v_mov_b32_dpp v67, v61 quad_perm:[2,3,0,1] row_mask:0xf bank_mask:0xf bound_ctrl:1
	v_med3_i32 v61, v61, v67, v123
	v_mov_b32_dpp v67, v64 quad_perm:[2,3,0,1] row_mask:0xf bank_mask:0xf bound_ctrl:1
	v_med3_i32 v64, v64, v67, v124
	v_mov_b32_dpp v67, v61 quad_perm:[1,0,3,2] row_mask:0xf bank_mask:0xf bound_ctrl:1
	v_med3_i32 v61, v61, v67, v125
	v_mov_b32_dpp v67, v64 quad_perm:[1,0,3,2] row_mask:0xf bank_mask:0xf bound_ctrl:1
	v_med3_i32 v64, v64, v67, v126
	v_max_i32_e32 v61, v61, v64
	v_mov_b32_e32 v67, v61
	s_nop 1
	v_permlane32_swap_b32_e32 v61, v67
	v_med3_i32 v61, v61, v67, v127
	v_mov_b32_e32 v67, v61
	s_nop 1
	v_permlane16_swap_b32_e32 v61, v67
	v_med3_i32 v61, v61, v67, v117
	s_nop 1
	v_mov_b32_dpp v64, v61 row_ror:8 row_mask:0xf bank_mask:0xf bound_ctrl:1
	v_med3_i32 v61, v61, v64, v119
	s_nop 1
	v_mov_b32_dpp v64, v61 row_half_mirror row_mask:0xf bank_mask:0xf bound_ctrl:1
	s_nop 1
	v_mov_b32_dpp v67, v64 quad_perm:[3,2,1,0] row_mask:0xf bank_mask:0xf bound_ctrl:1
	v_med3_i32 v61, v61, v67, v121
	s_nop 1
	v_mov_b32_dpp v64, v61 quad_perm:[2,3,0,1] row_mask:0xf bank_mask:0xf bound_ctrl:1
	v_med3_i32 v61, v61, v64, v123
	s_nop 1
	v_mov_b32_dpp v64, v61 quad_perm:[1,0,3,2] row_mask:0xf bank_mask:0xf bound_ctrl:1
	v_med3_i32 v61, v61, v64, v125
	v_max_i32_dpp v64, v65, v65 quad_perm:[1,0,3,2] row_mask:0xf bank_mask:0xf bound_ctrl:1
	v_min_i32_dpp v65, v65, v65 quad_perm:[1,0,3,2] row_mask:0xf bank_mask:0xf bound_ctrl:1
	v_cndmask_b32_e64 v64, v65, v64, s[12:13]
	s_nop 0
	v_max_i32_dpp v65, v66, v66 quad_perm:[1,0,3,2] row_mask:0xf bank_mask:0xf bound_ctrl:1
	v_min_i32_dpp v66, v66, v66 quad_perm:[1,0,3,2] row_mask:0xf bank_mask:0xf bound_ctrl:1
	v_cndmask_b32_e64 v65, v66, v65, s[12:13]
	s_nop 0
	v_mov_b32_dpp v66, v64 quad_perm:[2,3,0,1] row_mask:0xf bank_mask:0xf bound_ctrl:1
	v_med3_i32 v64, v64, v66, v101
	v_mov_b32_dpp v66, v65 quad_perm:[2,3,0,1] row_mask:0xf bank_mask:0xf bound_ctrl:1
	v_med3_i32 v65, v65, v66, v101
	v_mov_b32_dpp v66, v64 quad_perm:[1,0,3,2] row_mask:0xf bank_mask:0xf bound_ctrl:1
	v_med3_i32 v64, v64, v66, v102
	v_mov_b32_dpp v66, v65 quad_perm:[1,0,3,2] row_mask:0xf bank_mask:0xf bound_ctrl:1
	v_med3_i32 v65, v65, v66, v102
	v_mov_b32_dpp v66, v64 row_half_mirror row_mask:0xf bank_mask:0xf bound_ctrl:1
	s_nop 0
	v_mov_b32_dpp v67, v65 row_half_mirror row_mask:0xf bank_mask:0xf bound_ctrl:1
	v_mov_b32_dpp v68, v66 quad_perm:[3,2,1,0] row_mask:0xf bank_mask:0xf bound_ctrl:1
	v_med3_i32 v64, v64, v68, v103
	v_mov_b32_dpp v66, v67 quad_perm:[3,2,1,0] row_mask:0xf bank_mask:0xf bound_ctrl:1
	v_med3_i32 v65, v65, v66, v103
	v_mov_b32_dpp v66, v64 quad_perm:[2,3,0,1] row_mask:0xf bank_mask:0xf bound_ctrl:1
	v_med3_i32 v64, v64, v66, v104
	v_mov_b32_dpp v66, v65 quad_perm:[2,3,0,1] row_mask:0xf bank_mask:0xf bound_ctrl:1
	v_med3_i32 v65, v65, v66, v104
	v_mov_b32_dpp v66, v64 quad_perm:[1,0,3,2] row_mask:0xf bank_mask:0xf bound_ctrl:1
	v_med3_i32 v64, v64, v66, v105
	v_mov_b32_dpp v66, v65 quad_perm:[1,0,3,2] row_mask:0xf bank_mask:0xf bound_ctrl:1
	v_med3_i32 v65, v65, v66, v105
	v_mov_b32_dpp v66, v64 row_ror:8 row_mask:0xf bank_mask:0xf bound_ctrl:1
	v_med3_i32 v64, v64, v66, v106
	v_mov_b32_dpp v66, v65 row_ror:8 row_mask:0xf bank_mask:0xf bound_ctrl:1
	v_med3_i32 v65, v65, v66, v106
	v_mov_b32_dpp v66, v64 row_half_mirror row_mask:0xf bank_mask:0xf bound_ctrl:1
	s_nop 0
	v_mov_b32_dpp v67, v65 row_half_mirror row_mask:0xf bank_mask:0xf bound_ctrl:1
	v_mov_b32_dpp v68, v66 quad_perm:[3,2,1,0] row_mask:0xf bank_mask:0xf bound_ctrl:1
	v_med3_i32 v64, v64, v68, v107
	v_mov_b32_dpp v66, v67 quad_perm:[3,2,1,0] row_mask:0xf bank_mask:0xf bound_ctrl:1
	v_med3_i32 v65, v65, v66, v107
	v_mov_b32_dpp v66, v64 quad_perm:[2,3,0,1] row_mask:0xf bank_mask:0xf bound_ctrl:1
	v_med3_i32 v64, v64, v66, v108
	v_mov_b32_dpp v66, v65 quad_perm:[2,3,0,1] row_mask:0xf bank_mask:0xf bound_ctrl:1
	v_med3_i32 v65, v65, v66, v108
	v_mov_b32_dpp v66, v64 quad_perm:[1,0,3,2] row_mask:0xf bank_mask:0xf bound_ctrl:1
	v_med3_i32 v64, v64, v66, v109
	v_mov_b32_dpp v66, v65 quad_perm:[1,0,3,2] row_mask:0xf bank_mask:0xf bound_ctrl:1
	v_med3_i32 v65, v65, v66, v109
	v_mov_b32_e32 v67, v64
	s_nop 1
	v_permlane16_swap_b32_e32 v64, v67
	v_med3_i32 v64, v64, v67, v110
	v_mov_b32_e32 v68, v65
	s_nop 1
	v_permlane16_swap_b32_e32 v65, v68
	v_med3_i32 v65, v65, v68, v110
	s_nop 0
	v_mov_b32_dpp v66, v64 row_ror:8 row_mask:0xf bank_mask:0xf bound_ctrl:1
	v_med3_i32 v64, v64, v66, v111
	v_mov_b32_dpp v66, v65 row_ror:8 row_mask:0xf bank_mask:0xf bound_ctrl:1
	v_med3_i32 v65, v65, v66, v111
	v_mov_b32_dpp v66, v64 row_half_mirror row_mask:0xf bank_mask:0xf bound_ctrl:1
	s_nop 0
	v_mov_b32_dpp v67, v65 row_half_mirror row_mask:0xf bank_mask:0xf bound_ctrl:1
	v_mov_b32_dpp v68, v66 quad_perm:[3,2,1,0] row_mask:0xf bank_mask:0xf bound_ctrl:1
	v_med3_i32 v64, v64, v68, v112
	v_mov_b32_dpp v66, v67 quad_perm:[3,2,1,0] row_mask:0xf bank_mask:0xf bound_ctrl:1
	v_med3_i32 v65, v65, v66, v112
	v_mov_b32_dpp v66, v64 quad_perm:[2,3,0,1] row_mask:0xf bank_mask:0xf bound_ctrl:1
	v_med3_i32 v64, v64, v66, v113
	v_mov_b32_dpp v66, v65 quad_perm:[2,3,0,1] row_mask:0xf bank_mask:0xf bound_ctrl:1
	v_med3_i32 v65, v65, v66, v113
	v_mov_b32_dpp v66, v64 quad_perm:[1,0,3,2] row_mask:0xf bank_mask:0xf bound_ctrl:1
	v_med3_i32 v64, v64, v66, v114
	v_mov_b32_dpp v66, v65 quad_perm:[1,0,3,2] row_mask:0xf bank_mask:0xf bound_ctrl:1
	v_med3_i32 v65, v65, v66, v114
	v_mov_b32_e32 v67, v64
	s_nop 1
	v_permlane32_swap_b32_e32 v64, v67
	v_med3_i32 v64, v64, v67, v115
	v_mov_b32_e32 v68, v65
	s_nop 1
	v_permlane32_swap_b32_e32 v65, v68
	v_med3_i32 v65, v65, v68, v116
	v_mov_b32_e32 v67, v64
	s_nop 1
	v_permlane16_swap_b32_e32 v64, v67
	v_med3_i32 v64, v64, v67, v117
	v_mov_b32_e32 v68, v65
	s_nop 1
	v_permlane16_swap_b32_e32 v65, v68
	v_med3_i32 v65, v65, v68, v118
	s_nop 0
	v_mov_b32_dpp v66, v64 row_ror:8 row_mask:0xf bank_mask:0xf bound_ctrl:1
	v_med3_i32 v64, v64, v66, v119
	v_mov_b32_dpp v66, v65 row_ror:8 row_mask:0xf bank_mask:0xf bound_ctrl:1
	v_med3_i32 v65, v65, v66, v120
	v_mov_b32_dpp v66, v64 row_half_mirror row_mask:0xf bank_mask:0xf bound_ctrl:1
	s_nop 0
	v_mov_b32_dpp v67, v65 row_half_mirror row_mask:0xf bank_mask:0xf bound_ctrl:1
	v_mov_b32_dpp v68, v66 quad_perm:[3,2,1,0] row_mask:0xf bank_mask:0xf bound_ctrl:1
	v_med3_i32 v64, v64, v68, v121
	v_mov_b32_dpp v66, v67 quad_perm:[3,2,1,0] row_mask:0xf bank_mask:0xf bound_ctrl:1
	v_med3_i32 v65, v65, v66, v122
	v_mov_b32_dpp v66, v64 quad_perm:[2,3,0,1] row_mask:0xf bank_mask:0xf bound_ctrl:1
	v_med3_i32 v64, v64, v66, v123
	v_mov_b32_dpp v66, v65 quad_perm:[2,3,0,1] row_mask:0xf bank_mask:0xf bound_ctrl:1
	v_med3_i32 v65, v65, v66, v124
	v_mov_b32_dpp v66, v64 quad_perm:[1,0,3,2] row_mask:0xf bank_mask:0xf bound_ctrl:1
	v_med3_i32 v64, v64, v66, v125
	v_mov_b32_dpp v66, v65 quad_perm:[1,0,3,2] row_mask:0xf bank_mask:0xf bound_ctrl:1
	v_med3_i32 v65, v65, v66, v126
	v_max_i32_e32 v64, v64, v65
	v_mov_b32_e32 v66, v64
	s_nop 1
	v_permlane32_swap_b32_e32 v64, v66
	v_med3_i32 v64, v64, v66, v127
	v_mov_b32_e32 v66, v64
	s_nop 1
	v_permlane16_swap_b32_e32 v64, v66
	v_med3_i32 v64, v64, v66, v117
	s_nop 1
	v_mov_b32_dpp v65, v64 row_ror:8 row_mask:0xf bank_mask:0xf bound_ctrl:1
	v_med3_i32 v64, v64, v65, v119
	s_nop 1
	v_mov_b32_dpp v65, v64 row_half_mirror row_mask:0xf bank_mask:0xf bound_ctrl:1
	s_nop 1
	v_mov_b32_dpp v66, v65 quad_perm:[3,2,1,0] row_mask:0xf bank_mask:0xf bound_ctrl:1
	v_med3_i32 v64, v64, v66, v121
	s_nop 1
	v_mov_b32_dpp v65, v64 quad_perm:[2,3,0,1] row_mask:0xf bank_mask:0xf bound_ctrl:1
	v_med3_i32 v64, v64, v65, v123
	s_nop 1
	v_mov_b32_dpp v65, v64 quad_perm:[1,0,3,2] row_mask:0xf bank_mask:0xf bound_ctrl:1
	v_med3_i32 v64, v64, v65, v125
	v_bitop3_b32 v65, v61, s78, v61 bitop3:0xc
	v_bitop3_b32 v61, v61, v166, 63 bitop3:0xce
	v_lshlrev_b32_e32 v61, 2, v61
	ds_bpermute_b32 v59, v61, v59
	ds_bpermute_b32 v61, v61, v62
	v_bitop3_b32 v62, v64, v166, 63 bitop3:0xce
	v_lshlrev_b32_e32 v62, 2, v62
	ds_bpermute_b32 v63, v62, v63
	ds_bpermute_b32 v60, v62, v60
	v_bitop3_b32 v62, v64, s78, v64 bitop3:0xc
	v_cmp_gt_u32_e32 vcc, 64, v65
	s_waitcnt lgkmcnt(2)
	s_nop 0
	v_cndmask_b32_e32 v59, v61, v59, vcc
	v_cmp_gt_u32_e32 vcc, 64, v62
	ds_bpermute_b32 v59, v167, v59
	ds_bpermute_b32 v62, v168, v62
	s_waitcnt lgkmcnt(2)
	v_cndmask_b32_e32 v60, v60, v63, vcc
	ds_bpermute_b32 v60, v168, v60
	s_waitcnt lgkmcnt(0)
	v_add_f32_e32 v59, v59, v60
	v_ashrrev_i32_e32 v60, 31, v59
	v_and_b32_e32 v60, 0x7fffffc0, v60
	v_and_b32_e32 v61, 0xffffffc0, v59
	v_bitop3_b32 v60, v60, v165, v61 bitop3:0xde
	v_cndmask_b32_e64 v60, v60, v173, s[4:5]
	s_nop 1
	v_mov_b32_dpp v61, v60 quad_perm:[1,0,3,2] row_mask:0xf bank_mask:0xf bound_ctrl:1
	v_med3_i32 v60, v60, v61, v100
	s_nop 1
	v_mov_b32_dpp v61, v60 quad_perm:[2,3,0,1] row_mask:0xf bank_mask:0xf bound_ctrl:1
	v_med3_i32 v60, v60, v61, v101
	s_nop 1
	v_mov_b32_dpp v61, v60 quad_perm:[1,0,3,2] row_mask:0xf bank_mask:0xf bound_ctrl:1
	v_med3_i32 v60, v60, v61, v102
	s_nop 1
	v_mov_b32_dpp v61, v60 row_half_mirror row_mask:0xf bank_mask:0xf bound_ctrl:1
	s_nop 1
	v_mov_b32_dpp v63, v61 quad_perm:[3,2,1,0] row_mask:0xf bank_mask:0xf bound_ctrl:1
	v_med3_i32 v60, v60, v63, v103
	s_nop 1
	v_mov_b32_dpp v61, v60 quad_perm:[2,3,0,1] row_mask:0xf bank_mask:0xf bound_ctrl:1
	v_med3_i32 v60, v60, v61, v104
	s_nop 1
	v_mov_b32_dpp v61, v60 quad_perm:[1,0,3,2] row_mask:0xf bank_mask:0xf bound_ctrl:1
	v_med3_i32 v60, v60, v61, v105
	s_nop 1
	v_mov_b32_dpp v61, v60 row_ror:8 row_mask:0xf bank_mask:0xf bound_ctrl:1
	v_med3_i32 v60, v60, v61, v106
	s_nop 1
	v_mov_b32_dpp v61, v60 row_half_mirror row_mask:0xf bank_mask:0xf bound_ctrl:1
	s_nop 1
	v_mov_b32_dpp v63, v61 quad_perm:[3,2,1,0] row_mask:0xf bank_mask:0xf bound_ctrl:1
	v_med3_i32 v60, v60, v63, v107
	s_nop 1
	v_mov_b32_dpp v61, v60 quad_perm:[2,3,0,1] row_mask:0xf bank_mask:0xf bound_ctrl:1
	v_med3_i32 v60, v60, v61, v108
	s_nop 1
	v_mov_b32_dpp v61, v60 quad_perm:[1,0,3,2] row_mask:0xf bank_mask:0xf bound_ctrl:1
	v_med3_i32 v60, v60, v61, v109
	v_mov_b32_e32 v63, v60
	s_nop 1
	v_permlane16_swap_b32_e32 v60, v63
	v_med3_i32 v60, v60, v63, v110
	s_nop 1
	v_mov_b32_dpp v61, v60 row_ror:8 row_mask:0xf bank_mask:0xf bound_ctrl:1
	v_med3_i32 v60, v60, v61, v111
	s_nop 1
	v_mov_b32_dpp v61, v60 row_half_mirror row_mask:0xf bank_mask:0xf bound_ctrl:1
	s_nop 1
	v_mov_b32_dpp v63, v61 quad_perm:[3,2,1,0] row_mask:0xf bank_mask:0xf bound_ctrl:1
	v_med3_i32 v60, v60, v63, v112
	s_nop 1
	v_mov_b32_dpp v61, v60 quad_perm:[2,3,0,1] row_mask:0xf bank_mask:0xf bound_ctrl:1
	v_med3_i32 v60, v60, v61, v113
	s_nop 1
	v_mov_b32_dpp v61, v60 quad_perm:[1,0,3,2] row_mask:0xf bank_mask:0xf bound_ctrl:1
	v_med3_i32 v60, v60, v61, v114
	v_mov_b32_e32 v63, v60
	s_nop 1
	v_permlane32_swap_b32_e32 v60, v63
	v_med3_i32 v60, v60, v63, v127
	v_mov_b32_e32 v63, v60
	s_nop 1
	v_permlane16_swap_b32_e32 v60, v63
	v_med3_i32 v60, v60, v63, v117
	s_nop 1
	v_mov_b32_dpp v61, v60 row_ror:8 row_mask:0xf bank_mask:0xf bound_ctrl:1
	v_med3_i32 v60, v60, v61, v119
	s_nop 1
	v_mov_b32_dpp v61, v60 row_half_mirror row_mask:0xf bank_mask:0xf bound_ctrl:1
	s_nop 1
	v_mov_b32_dpp v63, v61 quad_perm:[3,2,1,0] row_mask:0xf bank_mask:0xf bound_ctrl:1
	v_med3_i32 v60, v60, v63, v121
	s_nop 1
	v_mov_b32_dpp v61, v60 quad_perm:[2,3,0,1] row_mask:0xf bank_mask:0xf bound_ctrl:1
	v_med3_i32 v60, v60, v61, v123
	s_nop 1
	v_mov_b32_dpp v61, v60 quad_perm:[1,0,3,2] row_mask:0xf bank_mask:0xf bound_ctrl:1
	v_med3_i32 v60, v60, v61, v125
	v_and_or_b32 v60, v60, 63, v166
	v_lshlrev_b32_e32 v60, 2, v60
	v_xor_b32_e32 v60, 0xfc, v60
	ds_bpermute_b32 v59, v60, v59
	ds_bpermute_b32 v61, v167, v65
	s_waitcnt lgkmcnt(1)
	v_readlane_b32 s33, v59, 0
	s_nop 1
	v_subrev_f32_e32 v59, s33, v59
	v_mul_f32_e32 v59, v24, v59
	v_mul_f32_e32 v59, 0x3fb8aa3b, v59
	v_exp_f32_e32 v59, v59
	s_waitcnt lgkmcnt(0)
	v_lshl_add_u32 v61, v61, 7, v62
	ds_bpermute_b32 v60, v60, v61
	v_cndmask_b32_e64 v61, 0, v59, s[54:55]
	s_nop 1
	v_add_f32_dpp v61, v61, v61 row_ror:8 row_mask:0xf bank_mask:0xf bound_ctrl:1
	s_nop 1
	v_mov_b32_dpp v62, v61 row_half_mirror row_mask:0xf bank_mask:0xf bound_ctrl:1
	s_nop 1
	v_add_f32_dpp v61, v62, v61 quad_perm:[3,2,1,0] row_mask:0xf bank_mask:0xf bound_ctrl:1
	s_nop 1
	v_add_f32_dpp v61, v61, v61 quad_perm:[2,3,0,1] row_mask:0xf bank_mask:0xf bound_ctrl:1
	s_nop 1
	v_mov_b32_dpp v62, v61 quad_perm:[1,0,3,2] row_mask:0xf bank_mask:0xf bound_ctrl:1
	s_and_saveexec_b64 s[66:67], s[54:55]
	s_cbranch_execz .LBB0_924
	v_add_f32_e32 v61, v61, v62
	v_div_scale_f32 v62, s[68:69], v61, v61, v59
	v_rcp_f32_e32 v63, v62
	v_div_scale_f32 v64, vcc, v59, v61, v59
	v_fma_f32 v65, -v62, v63, 1.0
	v_fmac_f32_e32 v63, v65, v63
	v_mul_f32_e32 v65, v64, v63
	v_fma_f32 v66, -v62, v65, v64
	v_fmac_f32_e32 v65, v66, v63
	v_fma_f32 v62, -v62, v65, v64
	v_div_fmas_f32 v62, v62, v63, v65
	v_div_fixup_f32 v59, v62, v61, v59
	s_waitcnt lgkmcnt(0)
	ds_write2st64_b32 v28, v60, v59 offset1:2
.LBB0_924:
	s_or_b64 exec, exec, s[66:67]
	v_add_co_u32_e32 v2, vcc, 0x8008000, v2
	s_nop 1
	v_addc_co_u32_e32 v3, vcc, 0, v3, vcc
	global_load_dword v59, v[2:3], off offset:1024
	s_waitcnt lgkmcnt(0)
	global_load_dword v60, v[2:3], off offset:1280
	global_load_dword v61, v[2:3], off offset:1536
	s_nop 0
	global_load_dword v2, v[2:3], off offset:1792
	s_waitcnt vmcnt(3)
	v_ashrrev_i32_e32 v3, 31, v59
	v_and_b32_e32 v62, 0xffffff80, v59
	s_waitcnt vmcnt(2)
	v_ashrrev_i32_e32 v63, 31, v60
	s_waitcnt vmcnt(1)
	v_ashrrev_i32_e32 v65, 31, v61
	v_and_b32_e32 v3, 0x7fffff80, v3
	v_and_b32_e32 v64, 0xffffff80, v60
	v_and_b32_e32 v66, 0xffffff80, v61
	v_and_b32_e32 v63, 0x7fffff80, v63
	v_and_b32_e32 v65, 0x7fffff80, v65
	v_bitop3_b32 v3, v3, v164, v62 bitop3:0xde
	v_bitop3_b32 v62, v63, v165, v64 bitop3:0xde
	v_bitop3_b32 v63, v65, v164, v66 bitop3:0xde
	v_mov_b32_dpp v65, v3 quad_perm:[1,0,3,2] row_mask:0xf bank_mask:0xf bound_ctrl:1
	v_mov_b32_dpp v66, v62 quad_perm:[1,0,3,2] row_mask:0xf bank_mask:0xf bound_ctrl:1
	v_med3_i32 v3, v3, v65, v100
	v_med3_i32 v62, v62, v66, v100
	s_waitcnt vmcnt(0)
	v_ashrrev_i32_e32 v67, 31, v2
	v_mov_b32_dpp v65, v3 quad_perm:[2,3,0,1] row_mask:0xf bank_mask:0xf bound_ctrl:1
	v_mov_b32_dpp v66, v62 quad_perm:[2,3,0,1] row_mask:0xf bank_mask:0xf bound_ctrl:1
	v_med3_i32 v3, v3, v65, v101
	v_med3_i32 v62, v62, v66, v101
	v_and_b32_e32 v68, 0xffffff80, v2
	v_mov_b32_dpp v65, v3 quad_perm:[1,0,3,2] row_mask:0xf bank_mask:0xf bound_ctrl:1
	v_mov_b32_dpp v66, v62 quad_perm:[1,0,3,2] row_mask:0xf bank_mask:0xf bound_ctrl:1
	v_med3_i32 v3, v3, v65, v102
	v_and_b32_e32 v67, 0x7fffff80, v67
	v_med3_i32 v62, v62, v66, v102
	v_mov_b32_dpp v65, v3 row_half_mirror row_mask:0xf bank_mask:0xf bound_ctrl:1
	v_bitop3_b32 v64, v67, v165, v68 bitop3:0xde
	v_mov_b32_dpp v66, v62 row_half_mirror row_mask:0xf bank_mask:0xf bound_ctrl:1
	v_mov_b32_dpp v67, v65 quad_perm:[3,2,1,0] row_mask:0xf bank_mask:0xf bound_ctrl:1
	s_nop 0
	v_mov_b32_dpp v65, v66 quad_perm:[3,2,1,0] row_mask:0xf bank_mask:0xf bound_ctrl:1
	v_med3_i32 v3, v3, v67, v103
	v_med3_i32 v62, v62, v65, v103
	s_nop 0
	v_mov_b32_dpp v65, v3 quad_perm:[2,3,0,1] row_mask:0xf bank_mask:0xf bound_ctrl:1
	v_mov_b32_dpp v66, v62 quad_perm:[2,3,0,1] row_mask:0xf bank_mask:0xf bound_ctrl:1
	v_med3_i32 v3, v3, v65, v104
	v_med3_i32 v62, v62, v66, v104
	s_nop 0
	v_mov_b32_dpp v65, v3 quad_perm:[1,0,3,2] row_mask:0xf bank_mask:0xf bound_ctrl:1
	v_mov_b32_dpp v66, v62 quad_perm:[1,0,3,2] row_mask:0xf bank_mask:0xf bound_ctrl:1
	v_med3_i32 v3, v3, v65, v105
	v_med3_i32 v62, v62, v66, v105
	s_nop 0
	v_mov_b32_dpp v65, v3 row_ror:8 row_mask:0xf bank_mask:0xf bound_ctrl:1
	v_mov_b32_dpp v66, v62 row_ror:8 row_mask:0xf bank_mask:0xf bound_ctrl:1
	v_med3_i32 v3, v3, v65, v106
	v_med3_i32 v62, v62, v66, v106
	s_nop 0
	v_mov_b32_dpp v65, v3 row_half_mirror row_mask:0xf bank_mask:0xf bound_ctrl:1
	v_mov_b32_dpp v66, v62 row_half_mirror row_mask:0xf bank_mask:0xf bound_ctrl:1
	s_nop 0
	v_mov_b32_dpp v67, v65 quad_perm:[3,2,1,0] row_mask:0xf bank_mask:0xf bound_ctrl:1
	v_mov_b32_dpp v65, v66 quad_perm:[3,2,1,0] row_mask:0xf bank_mask:0xf bound_ctrl:1
	v_med3_i32 v3, v3, v67, v107
	v_med3_i32 v62, v62, v65, v107
	s_nop 0
	v_mov_b32_dpp v65, v3 quad_perm:[2,3,0,1] row_mask:0xf bank_mask:0xf bound_ctrl:1
	v_mov_b32_dpp v66, v62 quad_perm:[2,3,0,1] row_mask:0xf bank_mask:0xf bound_ctrl:1
	v_med3_i32 v3, v3, v65, v108
	v_med3_i32 v62, v62, v66, v108
	s_nop 0
	v_mov_b32_dpp v65, v3 quad_perm:[1,0,3,2] row_mask:0xf bank_mask:0xf bound_ctrl:1
	v_mov_b32_dpp v66, v62 quad_perm:[1,0,3,2] row_mask:0xf bank_mask:0xf bound_ctrl:1
	v_med3_i32 v3, v3, v65, v109
	v_med3_i32 v62, v62, v66, v109
	v_mov_b32_e32 v65, v3
	v_mov_b32_e32 v66, v3
	v_mov_b32_e32 v67, v62
	v_mov_b32_e32 v68, v62
	v_permlane16_swap_b32_e32 v65, v66
	s_nop 0
	v_permlane16_swap_b32_e32 v67, v68
	v_cndmask_b32_e64 v65, v65, v66, s[6:7]
	v_cndmask_b32_e64 v66, v67, v68, s[6:7]
	v_max_i32_e32 v67, v3, v65
	v_min_i32_e32 v3, v3, v65
	v_cndmask_b32_e64 v3, v3, v67, s[42:43]
	v_med3_i32 v62, v62, v66, v110
	s_nop 0
	v_mov_b32_dpp v65, v3 row_ror:8 row_mask:0xf bank_mask:0xf bound_ctrl:1
	v_mov_b32_dpp v66, v62 row_ror:8 row_mask:0xf bank_mask:0xf bound_ctrl:1
	v_med3_i32 v3, v3, v65, v111
	v_med3_i32 v62, v62, v66, v111
	s_nop 0
	v_mov_b32_dpp v65, v3 row_half_mirror row_mask:0xf bank_mask:0xf bound_ctrl:1
	v_mov_b32_dpp v66, v62 row_half_mirror row_mask:0xf bank_mask:0xf bound_ctrl:1
	s_nop 0
	v_mov_b32_dpp v67, v65 quad_perm:[3,2,1,0] row_mask:0xf bank_mask:0xf bound_ctrl:1
	v_mov_b32_dpp v65, v66 quad_perm:[3,2,1,0] row_mask:0xf bank_mask:0xf bound_ctrl:1
	v_med3_i32 v3, v3, v67, v112
	v_med3_i32 v62, v62, v65, v112
	s_nop 0
	v_mov_b32_dpp v65, v3 quad_perm:[2,3,0,1] row_mask:0xf bank_mask:0xf bound_ctrl:1
	v_med3_i32 v3, v3, v65, v113
	v_mov_b32_dpp v65, v62 quad_perm:[2,3,0,1] row_mask:0xf bank_mask:0xf bound_ctrl:1
	v_med3_i32 v62, v62, v65, v113
	v_mov_b32_dpp v65, v3 quad_perm:[1,0,3,2] row_mask:0xf bank_mask:0xf bound_ctrl:1
	v_med3_i32 v3, v3, v65, v114
	v_mov_b32_dpp v65, v62 quad_perm:[1,0,3,2] row_mask:0xf bank_mask:0xf bound_ctrl:1
	v_med3_i32 v62, v62, v65, v114
	v_mov_b32_e32 v66, v3
	s_nop 1
	v_permlane32_swap_b32_e32 v3, v66
	v_med3_i32 v3, v3, v66, v115
	v_mov_b32_e32 v67, v62
	s_nop 1
	v_permlane32_swap_b32_e32 v62, v67
	v_med3_i32 v62, v62, v67, v116
	v_mov_b32_e32 v66, v3
	s_nop 1
	v_permlane16_swap_b32_e32 v3, v66
	v_med3_i32 v3, v3, v66, v117
	v_mov_b32_e32 v67, v62
	s_nop 1
	v_permlane16_swap_b32_e32 v62, v67
	v_med3_i32 v62, v62, v67, v118
	s_nop 0
	v_mov_b32_dpp v65, v3 row_ror:8 row_mask:0xf bank_mask:0xf bound_ctrl:1
	v_med3_i32 v3, v3, v65, v119
	v_mov_b32_dpp v65, v62 row_ror:8 row_mask:0xf bank_mask:0xf bound_ctrl:1
	v_med3_i32 v62, v62, v65, v120
	v_mov_b32_dpp v65, v3 row_half_mirror row_mask:0xf bank_mask:0xf bound_ctrl:1
	s_nop 0
	v_mov_b32_dpp v66, v62 row_half_mirror row_mask:0xf bank_mask:0xf bound_ctrl:1
	v_mov_b32_dpp v67, v65 quad_perm:[3,2,1,0] row_mask:0xf bank_mask:0xf bound_ctrl:1
	v_med3_i32 v3, v3, v67, v121
	v_mov_b32_dpp v65, v66 quad_perm:[3,2,1,0] row_mask:0xf bank_mask:0xf bound_ctrl:1
	v_med3_i32 v62, v62, v65, v122
	v_mov_b32_dpp v65, v3 quad_perm:[2,3,0,1] row_mask:0xf bank_mask:0xf bound_ctrl:1
	v_med3_i32 v3, v3, v65, v123
	v_mov_b32_dpp v65, v62 quad_perm:[2,3,0,1] row_mask:0xf bank_mask:0xf bound_ctrl:1
	v_med3_i32 v62, v62, v65, v124
	v_mov_b32_dpp v65, v3 quad_perm:[1,0,3,2] row_mask:0xf bank_mask:0xf bound_ctrl:1
	v_med3_i32 v3, v3, v65, v125
	v_mov_b32_dpp v65, v62 quad_perm:[1,0,3,2] row_mask:0xf bank_mask:0xf bound_ctrl:1
	v_med3_i32 v62, v62, v65, v126
	v_max_i32_e32 v3, v3, v62
	v_mov_b32_e32 v65, v3
	s_nop 1
	v_permlane32_swap_b32_e32 v3, v65
	v_med3_i32 v3, v3, v65, v127
	v_mov_b32_e32 v65, v3
	s_nop 1
	v_permlane16_swap_b32_e32 v3, v65
	v_med3_i32 v3, v3, v65, v117
	s_nop 1
	v_mov_b32_dpp v62, v3 row_ror:8 row_mask:0xf bank_mask:0xf bound_ctrl:1
	v_med3_i32 v3, v3, v62, v119
	s_nop 1
	v_mov_b32_dpp v62, v3 row_half_mirror row_mask:0xf bank_mask:0xf bound_ctrl:1
	s_nop 1
	v_mov_b32_dpp v65, v62 quad_perm:[3,2,1,0] row_mask:0xf bank_mask:0xf bound_ctrl:1
	v_med3_i32 v3, v3, v65, v121
	s_nop 1
	v_mov_b32_dpp v62, v3 quad_perm:[2,3,0,1] row_mask:0xf bank_mask:0xf bound_ctrl:1
	v_med3_i32 v3, v3, v62, v123
	s_nop 1
	v_mov_b32_dpp v62, v3 quad_perm:[1,0,3,2] row_mask:0xf bank_mask:0xf bound_ctrl:1
	v_med3_i32 v3, v3, v62, v125
	v_max_i32_dpp v62, v63, v63 quad_perm:[1,0,3,2] row_mask:0xf bank_mask:0xf bound_ctrl:1
	v_min_i32_dpp v63, v63, v63 quad_perm:[1,0,3,2] row_mask:0xf bank_mask:0xf bound_ctrl:1
	v_cndmask_b32_e64 v62, v63, v62, s[12:13]
	s_nop 0
	v_max_i32_dpp v63, v64, v64 quad_perm:[1,0,3,2] row_mask:0xf bank_mask:0xf bound_ctrl:1
	v_min_i32_dpp v64, v64, v64 quad_perm:[1,0,3,2] row_mask:0xf bank_mask:0xf bound_ctrl:1
	v_cndmask_b32_e64 v63, v64, v63, s[12:13]
	s_nop 0
	v_mov_b32_dpp v64, v62 quad_perm:[2,3,0,1] row_mask:0xf bank_mask:0xf bound_ctrl:1
	v_med3_i32 v62, v62, v64, v101
	v_mov_b32_dpp v64, v63 quad_perm:[2,3,0,1] row_mask:0xf bank_mask:0xf bound_ctrl:1
	v_med3_i32 v63, v63, v64, v101
	v_mov_b32_dpp v64, v62 quad_perm:[1,0,3,2] row_mask:0xf bank_mask:0xf bound_ctrl:1
	v_med3_i32 v62, v62, v64, v102
	v_mov_b32_dpp v64, v63 quad_perm:[1,0,3,2] row_mask:0xf bank_mask:0xf bound_ctrl:1
	v_med3_i32 v63, v63, v64, v102
	v_mov_b32_dpp v64, v62 row_half_mirror row_mask:0xf bank_mask:0xf bound_ctrl:1
	s_nop 0
	v_mov_b32_dpp v65, v63 row_half_mirror row_mask:0xf bank_mask:0xf bound_ctrl:1
	v_mov_b32_dpp v66, v64 quad_perm:[3,2,1,0] row_mask:0xf bank_mask:0xf bound_ctrl:1
	v_med3_i32 v62, v62, v66, v103
	v_mov_b32_dpp v64, v65 quad_perm:[3,2,1,0] row_mask:0xf bank_mask:0xf bound_ctrl:1
	v_med3_i32 v63, v63, v64, v103
	v_mov_b32_dpp v64, v62 quad_perm:[2,3,0,1] row_mask:0xf bank_mask:0xf bound_ctrl:1
	v_med3_i32 v62, v62, v64, v104
	v_mov_b32_dpp v64, v63 quad_perm:[2,3,0,1] row_mask:0xf bank_mask:0xf bound_ctrl:1
	v_med3_i32 v63, v63, v64, v104
	v_mov_b32_dpp v64, v62 quad_perm:[1,0,3,2] row_mask:0xf bank_mask:0xf bound_ctrl:1
	v_med3_i32 v62, v62, v64, v105
	v_mov_b32_dpp v64, v63 quad_perm:[1,0,3,2] row_mask:0xf bank_mask:0xf bound_ctrl:1
	v_med3_i32 v63, v63, v64, v105
	v_mov_b32_dpp v64, v62 row_ror:8 row_mask:0xf bank_mask:0xf bound_ctrl:1
	v_med3_i32 v62, v62, v64, v106
	v_mov_b32_dpp v64, v63 row_ror:8 row_mask:0xf bank_mask:0xf bound_ctrl:1
	v_med3_i32 v63, v63, v64, v106
	v_mov_b32_dpp v64, v62 row_half_mirror row_mask:0xf bank_mask:0xf bound_ctrl:1
	s_nop 0
	v_mov_b32_dpp v65, v63 row_half_mirror row_mask:0xf bank_mask:0xf bound_ctrl:1
	v_mov_b32_dpp v66, v64 quad_perm:[3,2,1,0] row_mask:0xf bank_mask:0xf bound_ctrl:1
	v_med3_i32 v62, v62, v66, v107
	v_mov_b32_dpp v64, v65 quad_perm:[3,2,1,0] row_mask:0xf bank_mask:0xf bound_ctrl:1
	v_med3_i32 v63, v63, v64, v107
	v_mov_b32_dpp v64, v62 quad_perm:[2,3,0,1] row_mask:0xf bank_mask:0xf bound_ctrl:1
	v_med3_i32 v62, v62, v64, v108
	v_mov_b32_dpp v64, v63 quad_perm:[2,3,0,1] row_mask:0xf bank_mask:0xf bound_ctrl:1
	v_med3_i32 v63, v63, v64, v108
	v_mov_b32_dpp v64, v62 quad_perm:[1,0,3,2] row_mask:0xf bank_mask:0xf bound_ctrl:1
	v_med3_i32 v62, v62, v64, v109
	v_mov_b32_dpp v64, v63 quad_perm:[1,0,3,2] row_mask:0xf bank_mask:0xf bound_ctrl:1
	v_med3_i32 v63, v63, v64, v109
	v_mov_b32_e32 v65, v62
	s_nop 1
	v_permlane16_swap_b32_e32 v62, v65
	v_med3_i32 v62, v62, v65, v110
	v_mov_b32_e32 v66, v63
	s_nop 1
	v_permlane16_swap_b32_e32 v63, v66
	v_med3_i32 v63, v63, v66, v110
	s_nop 0
	v_mov_b32_dpp v64, v62 row_ror:8 row_mask:0xf bank_mask:0xf bound_ctrl:1
	v_med3_i32 v62, v62, v64, v111
	v_mov_b32_dpp v64, v63 row_ror:8 row_mask:0xf bank_mask:0xf bound_ctrl:1
	v_med3_i32 v63, v63, v64, v111
	v_mov_b32_dpp v64, v62 row_half_mirror row_mask:0xf bank_mask:0xf bound_ctrl:1
	s_nop 0
	v_mov_b32_dpp v65, v63 row_half_mirror row_mask:0xf bank_mask:0xf bound_ctrl:1
	v_mov_b32_dpp v66, v64 quad_perm:[3,2,1,0] row_mask:0xf bank_mask:0xf bound_ctrl:1
	v_med3_i32 v62, v62, v66, v112
	v_mov_b32_dpp v64, v65 quad_perm:[3,2,1,0] row_mask:0xf bank_mask:0xf bound_ctrl:1
	v_med3_i32 v63, v63, v64, v112
	v_mov_b32_dpp v64, v62 quad_perm:[2,3,0,1] row_mask:0xf bank_mask:0xf bound_ctrl:1
	v_med3_i32 v62, v62, v64, v113
	v_mov_b32_dpp v64, v63 quad_perm:[2,3,0,1] row_mask:0xf bank_mask:0xf bound_ctrl:1
	v_med3_i32 v63, v63, v64, v113
	v_mov_b32_dpp v64, v62 quad_perm:[1,0,3,2] row_mask:0xf bank_mask:0xf bound_ctrl:1
	v_med3_i32 v62, v62, v64, v114
	v_mov_b32_dpp v64, v63 quad_perm:[1,0,3,2] row_mask:0xf bank_mask:0xf bound_ctrl:1
	v_med3_i32 v63, v63, v64, v114
	v_mov_b32_e32 v65, v62
	s_nop 1
	v_permlane32_swap_b32_e32 v62, v65
	v_med3_i32 v62, v62, v65, v115
	v_mov_b32_e32 v66, v63
	s_nop 1
	v_permlane32_swap_b32_e32 v63, v66
	v_med3_i32 v63, v63, v66, v116
	v_mov_b32_e32 v65, v62
	s_nop 1
	v_permlane16_swap_b32_e32 v62, v65
	v_med3_i32 v62, v62, v65, v117
	v_mov_b32_e32 v66, v63
	s_nop 1
	v_permlane16_swap_b32_e32 v63, v66
	v_med3_i32 v63, v63, v66, v118
	s_nop 0
	v_mov_b32_dpp v64, v62 row_ror:8 row_mask:0xf bank_mask:0xf bound_ctrl:1
	v_med3_i32 v62, v62, v64, v119
	v_mov_b32_dpp v64, v63 row_ror:8 row_mask:0xf bank_mask:0xf bound_ctrl:1
	v_med3_i32 v63, v63, v64, v120
	v_mov_b32_dpp v64, v62 row_half_mirror row_mask:0xf bank_mask:0xf bound_ctrl:1
	s_nop 0
	v_mov_b32_dpp v65, v63 row_half_mirror row_mask:0xf bank_mask:0xf bound_ctrl:1
	v_mov_b32_dpp v66, v64 quad_perm:[3,2,1,0] row_mask:0xf bank_mask:0xf bound_ctrl:1
	v_med3_i32 v62, v62, v66, v121
	v_mov_b32_dpp v64, v65 quad_perm:[3,2,1,0] row_mask:0xf bank_mask:0xf bound_ctrl:1
	v_med3_i32 v63, v63, v64, v122
	v_mov_b32_dpp v64, v62 quad_perm:[2,3,0,1] row_mask:0xf bank_mask:0xf bound_ctrl:1
	v_med3_i32 v62, v62, v64, v123
	v_mov_b32_dpp v64, v63 quad_perm:[2,3,0,1] row_mask:0xf bank_mask:0xf bound_ctrl:1
	v_med3_i32 v63, v63, v64, v124
	v_mov_b32_dpp v64, v62 quad_perm:[1,0,3,2] row_mask:0xf bank_mask:0xf bound_ctrl:1
	v_med3_i32 v62, v62, v64, v125
	v_mov_b32_dpp v64, v63 quad_perm:[1,0,3,2] row_mask:0xf bank_mask:0xf bound_ctrl:1
	v_med3_i32 v63, v63, v64, v126
	v_max_i32_e32 v62, v62, v63
	v_mov_b32_e32 v64, v62
	s_nop 1
	v_permlane32_swap_b32_e32 v62, v64
	v_med3_i32 v62, v62, v64, v127
	v_mov_b32_e32 v64, v62
	s_nop 1
	v_permlane16_swap_b32_e32 v62, v64
	v_med3_i32 v62, v62, v64, v117
	s_nop 1
	v_mov_b32_dpp v63, v62 row_ror:8 row_mask:0xf bank_mask:0xf bound_ctrl:1
	v_med3_i32 v62, v62, v63, v119
	s_nop 1
	v_mov_b32_dpp v63, v62 row_half_mirror row_mask:0xf bank_mask:0xf bound_ctrl:1
	s_nop 1
	v_mov_b32_dpp v64, v63 quad_perm:[3,2,1,0] row_mask:0xf bank_mask:0xf bound_ctrl:1
	v_med3_i32 v62, v62, v64, v121
	s_nop 1
	v_mov_b32_dpp v63, v62 quad_perm:[2,3,0,1] row_mask:0xf bank_mask:0xf bound_ctrl:1
	v_med3_i32 v62, v62, v63, v123
	s_nop 1
	v_mov_b32_dpp v63, v62 quad_perm:[1,0,3,2] row_mask:0xf bank_mask:0xf bound_ctrl:1
	v_med3_i32 v62, v62, v63, v125
	v_bitop3_b32 v63, v3, s78, v3 bitop3:0xc
	v_bitop3_b32 v3, v3, v166, 63 bitop3:0xce
	v_lshlrev_b32_e32 v3, 2, v3
	ds_bpermute_b32 v59, v3, v59
	ds_bpermute_b32 v3, v3, v60
	v_bitop3_b32 v60, v62, v166, 63 bitop3:0xce
	v_lshlrev_b32_e32 v60, 2, v60
	ds_bpermute_b32 v61, v60, v61
	ds_bpermute_b32 v2, v60, v2
	v_bitop3_b32 v60, v62, s78, v62 bitop3:0xc
	v_cmp_gt_u32_e32 vcc, 64, v63
	s_waitcnt lgkmcnt(2)
	s_nop 0
	v_cndmask_b32_e32 v3, v3, v59, vcc
	v_cmp_gt_u32_e32 vcc, 64, v60
	ds_bpermute_b32 v3, v167, v3
	ds_bpermute_b32 v60, v168, v60
	s_waitcnt lgkmcnt(2)
	v_cndmask_b32_e32 v2, v2, v61, vcc
	ds_bpermute_b32 v2, v168, v2
	s_waitcnt lgkmcnt(0)
	v_add_f32_e32 v2, v3, v2
	v_ashrrev_i32_e32 v3, 31, v2
	v_and_b32_e32 v3, 0x7fffffc0, v3
	v_and_b32_e32 v59, 0xffffffc0, v2
	v_bitop3_b32 v3, v3, v165, v59 bitop3:0xde
	v_cndmask_b32_e64 v3, v3, v173, s[4:5]
	s_nop 1
	v_mov_b32_dpp v59, v3 quad_perm:[1,0,3,2] row_mask:0xf bank_mask:0xf bound_ctrl:1
	v_med3_i32 v3, v3, v59, v100
	s_nop 1
	v_mov_b32_dpp v59, v3 quad_perm:[2,3,0,1] row_mask:0xf bank_mask:0xf bound_ctrl:1
	v_med3_i32 v3, v3, v59, v101
	s_nop 1
	v_mov_b32_dpp v59, v3 quad_perm:[1,0,3,2] row_mask:0xf bank_mask:0xf bound_ctrl:1
	v_med3_i32 v3, v3, v59, v102
	s_nop 1
	v_mov_b32_dpp v59, v3 row_half_mirror row_mask:0xf bank_mask:0xf bound_ctrl:1
	s_nop 1
	v_mov_b32_dpp v61, v59 quad_perm:[3,2,1,0] row_mask:0xf bank_mask:0xf bound_ctrl:1
	v_med3_i32 v3, v3, v61, v103
	s_nop 1
	v_mov_b32_dpp v59, v3 quad_perm:[2,3,0,1] row_mask:0xf bank_mask:0xf bound_ctrl:1
	v_med3_i32 v3, v3, v59, v104
	s_nop 1
	v_mov_b32_dpp v59, v3 quad_perm:[1,0,3,2] row_mask:0xf bank_mask:0xf bound_ctrl:1
	v_med3_i32 v3, v3, v59, v105
	s_nop 1
	v_mov_b32_dpp v59, v3 row_ror:8 row_mask:0xf bank_mask:0xf bound_ctrl:1
	v_med3_i32 v3, v3, v59, v106
	s_nop 1
	v_mov_b32_dpp v59, v3 row_half_mirror row_mask:0xf bank_mask:0xf bound_ctrl:1
	s_nop 1
	v_mov_b32_dpp v61, v59 quad_perm:[3,2,1,0] row_mask:0xf bank_mask:0xf bound_ctrl:1
	v_med3_i32 v3, v3, v61, v107
	s_nop 1
	v_mov_b32_dpp v59, v3 quad_perm:[2,3,0,1] row_mask:0xf bank_mask:0xf bound_ctrl:1
	v_med3_i32 v3, v3, v59, v108
	s_nop 1
	v_mov_b32_dpp v59, v3 quad_perm:[1,0,3,2] row_mask:0xf bank_mask:0xf bound_ctrl:1
	v_med3_i32 v3, v3, v59, v109
	v_mov_b32_e32 v61, v3
	s_nop 1
	v_permlane16_swap_b32_e32 v3, v61
	v_med3_i32 v3, v3, v61, v110
	s_nop 1
	v_mov_b32_dpp v59, v3 row_ror:8 row_mask:0xf bank_mask:0xf bound_ctrl:1
	v_med3_i32 v3, v3, v59, v111
	s_nop 1
	v_mov_b32_dpp v59, v3 row_half_mirror row_mask:0xf bank_mask:0xf bound_ctrl:1
	s_nop 1
	v_mov_b32_dpp v61, v59 quad_perm:[3,2,1,0] row_mask:0xf bank_mask:0xf bound_ctrl:1
	v_med3_i32 v3, v3, v61, v112
	s_nop 1
	v_mov_b32_dpp v59, v3 quad_perm:[2,3,0,1] row_mask:0xf bank_mask:0xf bound_ctrl:1
	v_med3_i32 v3, v3, v59, v113
	s_nop 1
	v_mov_b32_dpp v59, v3 quad_perm:[1,0,3,2] row_mask:0xf bank_mask:0xf bound_ctrl:1
	v_med3_i32 v3, v3, v59, v114
	v_mov_b32_e32 v61, v3
	s_nop 1
	v_permlane32_swap_b32_e32 v3, v61
	v_med3_i32 v3, v3, v61, v127
	v_mov_b32_e32 v61, v3
	s_nop 1
	v_permlane16_swap_b32_e32 v3, v61
	v_med3_i32 v3, v3, v61, v117
	s_nop 1
	v_mov_b32_dpp v59, v3 row_ror:8 row_mask:0xf bank_mask:0xf bound_ctrl:1
	v_med3_i32 v3, v3, v59, v119
	s_nop 1
	v_mov_b32_dpp v59, v3 row_half_mirror row_mask:0xf bank_mask:0xf bound_ctrl:1
	s_nop 1
	v_mov_b32_dpp v61, v59 quad_perm:[3,2,1,0] row_mask:0xf bank_mask:0xf bound_ctrl:1
	v_med3_i32 v3, v3, v61, v121
	s_nop 1
	v_mov_b32_dpp v59, v3 quad_perm:[2,3,0,1] row_mask:0xf bank_mask:0xf bound_ctrl:1
	v_med3_i32 v3, v3, v59, v123
	s_nop 1
	v_mov_b32_dpp v59, v3 quad_perm:[1,0,3,2] row_mask:0xf bank_mask:0xf bound_ctrl:1
	v_med3_i32 v3, v3, v59, v125
	v_and_or_b32 v3, v3, 63, v166
	v_lshlrev_b32_e32 v3, 2, v3
	v_xor_b32_e32 v3, 0xfc, v3
	ds_bpermute_b32 v2, v3, v2
	ds_bpermute_b32 v59, v167, v63
	s_waitcnt lgkmcnt(1)
	v_readlane_b32 s33, v2, 0
	s_nop 1
	v_subrev_f32_e32 v2, s33, v2
	v_mul_f32_e32 v2, v24, v2
	v_mul_f32_e32 v2, 0x3fb8aa3b, v2
	v_exp_f32_e32 v2, v2
	s_waitcnt lgkmcnt(0)
	v_lshl_add_u32 v59, v59, 7, v60
	ds_bpermute_b32 v3, v3, v59
	v_cndmask_b32_e64 v59, 0, v2, s[54:55]
	s_nop 1
	v_add_f32_dpp v59, v59, v59 row_ror:8 row_mask:0xf bank_mask:0xf bound_ctrl:1
	s_nop 1
	v_mov_b32_dpp v60, v59 row_half_mirror row_mask:0xf bank_mask:0xf bound_ctrl:1
	s_nop 1
	v_add_f32_dpp v59, v60, v59 quad_perm:[3,2,1,0] row_mask:0xf bank_mask:0xf bound_ctrl:1
	s_nop 1
	v_add_f32_dpp v59, v59, v59 quad_perm:[2,3,0,1] row_mask:0xf bank_mask:0xf bound_ctrl:1
	s_nop 1
	v_mov_b32_dpp v60, v59 quad_perm:[1,0,3,2] row_mask:0xf bank_mask:0xf bound_ctrl:1
	s_and_saveexec_b64 s[66:67], s[54:55]
	s_cbranch_execz .LBB0_921
	v_add_f32_e32 v59, v59, v60
	v_div_scale_f32 v60, s[68:69], v59, v59, v2
	v_rcp_f32_e32 v61, v60
	v_div_scale_f32 v62, vcc, v2, v59, v2
	v_fma_f32 v63, -v60, v61, 1.0
	v_fmac_f32_e32 v61, v63, v61
	v_mul_f32_e32 v63, v62, v61
	v_fma_f32 v64, -v60, v63, v62
	v_fmac_f32_e32 v63, v64, v61
	v_fma_f32 v60, -v60, v63, v62
	v_div_fmas_f32 v60, v60, v61, v63
	v_div_fixup_f32 v2, v60, v59, v2
	s_waitcnt lgkmcnt(0)
	ds_write2_b32 v28, v3, v2 offset0:16 offset1:144
	s_branch .LBB0_921
